# plus 64-byte alignment of the four 256x256 GEMM K-loop heads
# speedup vs baseline: 1.0176x; 1.0011x over previous
; #define LAS __attribute__((address_space(3)))
; #define GLDS_STAGE(st, kt_) do { \
;         _Pragma("unroll") for (int i_ = 0; i_ < FI; ++i_) { \
;             glds16(ap + (size_t)(32 * i_) * lda + (kt_) * 64, l3a + (st) + tid * 16 + i_ * 4096); \
;             glds16(bp + (size_t)(32 * i_) * ldb + (kt_) * 64, l3a + (st) + OPB + tid * 16 + i_ * 4096); } } while (0)
; #define GLDS_STAGE(st, kt_) do { \
;         _Pragma("unroll") for (int i_ = 0; i_ < 4; ++i_) { \
;             glds16(ap + (size_t)(64 * i_) * lda + (kt_) * 64, l3a + (st) + tid * 16 + i_ * 8192); \
;             glds16(bp + (size_t)(64 * i_) * ldb + (kt_) * 64, l3a + (st) + 32768 + tid * 16 + i_ * 8192); } } while (0)
; template <class Epi>
; DEV void gemm256_tile(const bf16_t* __restrict__ A, int lda, const bf16_t* __restrict__ Bt, int ldb, int K, unsigned char* lds, const Epi& epi) {
;     int tid = threadIdx.x; asm volatile("" : "+v"(tid)); const int lane = tid & 63, wid = tid >> 6;
;     const int wr = wid >> 2, wc = wid & 3, fr = lane & 15, fq = lane >> 4;
;     f32x4 acc[8][4];
; #pragma unroll
;     for (int i = 0; i < 8; ++i)
; #pragma unroll
;         for (int j = 0; j < 4; ++j) acc[i][j] = (f32x4){0.f, 0.f, 0.f, 0.f};
;     const int lrow = tid >> 3, lcs = (tid & 7) ^ (lrow & 7);
;     const bf16_t* ap = A + (size_t)lrow * lda + lcs * 8;
;     const bf16_t* bp = Bt + (size_t)lrow * ldb + lcs * 8;
;     const unsigned l3a = (unsigned)(size_t)(LAS unsigned char*)lds;
;     const int nk = K >> 6;
;     ...
;     GLDS_STAGE(0, 0);
;     const int aoff = (wr * 128 + fr) * 128, boff = 32768 + (wc * 64 + fr) * 128, sw = fr & 7;
.LBB0_173:
	s_and_b32 s19, s18, 7
	s_mulk_i32 s19, 0x60
	s_ashr_i32 s20, s18, 3
	s_add_i32 s19, s19, s20
	s_mul_hi_i32 s20, s19, 0x2aaaaaab
	s_lshr_b32 s21, s20, 31
	s_ashr_i32 s20, s20, 5
	s_add_i32 s20, s20, s21
	s_lshl_b32 s21, s20, 3
	s_mulk_i32 s20, 0xc0
	s_sub_i32 s19, s19, s20
	s_sext_i32_i16 s20, s19
	s_bfe_u32 s20, s20, 0x3001c
	s_add_i32 s22, s19, s20
	s_sext_i32_i16 s24, s22
	s_and_b32 s22, s22, 0xfff8
	s_sub_i32 s19, s19, s22
	v_mov_b32_e32 v150, v0
	s_sext_i32_i16 s19, s19
	s_add_i32 s19, s21, s19
	v_ashrrev_i32_e32 v10, 3, v150
	s_ashr_i32 s21, s24, 3
	v_xor_b32_e32 v8, v10, v150
	v_mad_i64_i32 v[2:3], s[22:23], s19, v148, v[166:167]
	v_mad_i64_i32 v[4:5], s[22:23], s21, v148, v[130:131]
	v_lshlrev_b32_e32 v8, 4, v8
	v_mad_i64_i32 v[2:3], s[22:23], v10, s13, v[2:3]
	v_and_b32_e32 v142, 0x70, v8
	v_mad_i64_i32 v[4:5], s[22:23], v10, s13, v[4:5]
	v_mad_i64_i32 v[6:7], s[22:23], v10, s13, 0
	v_lshl_add_u64 v[2:3], v[2:3], 0, v[142:143]
	v_lshl_add_u64 v[4:5], v[4:5], 0, v[142:143]
	v_lshlrev_b32_e32 v142, 4, v150
	v_add_u32_e32 v156, 0x8000, v142
	v_readfirstlane_b32 s22, v142
	s_mov_b32 s23, m0
	s_mov_b32 m0, s22
	s_nop 0
	global_load_lds_dwordx4 v[2:3], off
	s_mov_b32 m0, s23
	s_lshr_b32 s20, s24, 3
	v_readfirstlane_b32 s23, v156
	s_mov_b32 s24, m0
	s_mov_b32 m0, s23
	s_nop 0
	global_load_lds_dwordx4 v[4:5], off
	s_mov_b32 m0, s24
	v_lshl_add_u64 v[8:9], v[2:3], 0, s[4:5]
	s_add_i32 s23, s22, 0x2000
	s_mov_b32 s24, m0
	s_mov_b32 m0, s23
	s_nop 0
	global_load_lds_dwordx4 v[8:9], off
	s_mov_b32 m0, s24
	v_lshl_add_u64 v[8:9], v[4:5], 0, s[4:5]
	s_add_i32 s23, s22, 0xa000
	s_mov_b32 s24, m0
	s_mov_b32 m0, s23
	s_nop 0
	global_load_lds_dwordx4 v[8:9], off
	s_mov_b32 m0, s24
	v_lshl_add_u64 v[8:9], v[2:3], 0, s[6:7]
	s_add_i32 s23, s22, 0x4000
	s_mov_b32 s24, m0
	s_mov_b32 m0, s23
	s_nop 0
	global_load_lds_dwordx4 v[8:9], off
	s_mov_b32 m0, s24
	v_lshl_add_u64 v[8:9], v[4:5], 0, s[6:7]
	s_add_i32 s23, s22, 0xc000
	s_mov_b32 s24, m0
	s_mov_b32 m0, s23
	s_nop 0
	global_load_lds_dwordx4 v[8:9], off
	s_mov_b32 m0, s24
	v_lshl_add_u64 v[2:3], v[2:3], 0, s[8:9]
	s_add_i32 s23, s22, 0x6000
	s_mov_b32 s24, m0
	s_mov_b32 m0, s23
	s_nop 0
	global_load_lds_dwordx4 v[2:3], off
	s_mov_b32 m0, s24
	v_lshl_add_u64 v[2:3], v[4:5], 0, s[8:9]
	v_and_b32_e32 v151, 15, v150
	s_add_i32 s22, s22, 0xe000
	s_mov_b32 s23, m0
	s_mov_b32 m0, s22
	s_nop 0
	global_load_lds_dwordx4 v[2:3], off
	s_mov_b32 m0, s23
	v_ashrrev_i32_e32 v2, 1, v150
	v_and_or_b32 v154, v2, s16, v151
	v_lshlrev_b32_e32 v2, 7, v150
	v_lshrrev_b32_e32 v152, 4, v150
	v_bfe_u32 v153, v150, 4, 2
	v_and_b32_e32 v175, 0x6780, v2
	v_and_b32_e32 v2, 7, v150
	v_bitop3_b32 v3, v152, v2, 3 bitop3:0x6c
	v_bitop3_b32 v2, v153, v2, 4 bitop3:0x36
	v_bitop3_b32 v4, v10, 7, v150 bitop3:0x48
	v_lshlrev_b32_e32 v174, 4, v3
	v_lshlrev_b32_e32 v155, 4, v2
	v_mad_i64_i32 v[2:3], s[22:23], s19, v148, v[6:7]
	v_lshlrev_b32_e32 v4, 4, v4
	v_or_b32_e32 v2, v2, v4
	v_lshl_add_u64 v[144:145], v[136:137], 0, v[2:3]
	v_mad_i64_i32 v[2:3], s[22:23], s21, v148, v[6:7]
	v_or_b32_e32 v2, v2, v4
	v_lshlrev_b32_e32 v157, 7, v154
	v_lshl_add_u64 v[146:147], v[140:141], 0, v[2:3]
	s_mov_b32 s21, 0
	v_mov_b32_e32 v38, v143
	v_mov_b32_e32 v39, v143
	v_mov_b32_e32 v40, v143
	v_mov_b32_e32 v41, v143
	v_mov_b32_e32 v2, v143
	v_mov_b32_e32 v3, v143
	v_mov_b32_e32 v4, v143
	v_mov_b32_e32 v5, v143
	v_mov_b32_e32 v6, v143
	v_mov_b32_e32 v7, v143
	v_mov_b32_e32 v8, v143
	v_mov_b32_e32 v9, v143
	v_mov_b32_e32 v10, v143
	v_mov_b32_e32 v11, v143
	v_mov_b32_e32 v12, v143
	v_mov_b32_e32 v13, v143
	v_mov_b32_e32 v14, v143
	v_mov_b32_e32 v15, v143
	v_mov_b32_e32 v16, v143
	v_mov_b32_e32 v17, v143
	v_mov_b32_e32 v18, v143
	v_mov_b32_e32 v19, v143
	v_mov_b32_e32 v20, v143
	v_mov_b32_e32 v21, v143
	v_mov_b32_e32 v22, v143
	v_mov_b32_e32 v23, v143
	v_mov_b32_e32 v24, v143
	v_mov_b32_e32 v25, v143
	v_mov_b32_e32 v26, v143
	v_mov_b32_e32 v27, v143
	v_mov_b32_e32 v28, v143
	v_mov_b32_e32 v29, v143
	v_mov_b32_e32 v30, v143
	v_mov_b32_e32 v31, v143
	v_mov_b32_e32 v32, v143
	v_mov_b32_e32 v33, v143
	v_mov_b32_e32 v34, v143
	v_mov_b32_e32 v35, v143
	v_mov_b32_e32 v36, v143
	v_mov_b32_e32 v37, v143
	v_mov_b32_e32 v42, v143
	v_mov_b32_e32 v43, v143
	v_mov_b32_e32 v44, v143
	v_mov_b32_e32 v45, v143
	v_mov_b32_e32 v46, v143
	v_mov_b32_e32 v47, v143
	v_mov_b32_e32 v48, v143
	v_mov_b32_e32 v49, v143
	v_mov_b32_e32 v50, v143
	v_mov_b32_e32 v51, v143
	v_mov_b32_e32 v52, v143
	v_mov_b32_e32 v53, v143
	v_mov_b32_e32 v54, v143
	v_mov_b32_e32 v55, v143
	v_mov_b32_e32 v56, v143
	v_mov_b32_e32 v57, v143
	v_mov_b32_e32 v58, v143
	v_mov_b32_e32 v59, v143
	v_mov_b32_e32 v60, v143
	v_mov_b32_e32 v61, v143
	v_mov_b32_e32 v62, v143
	v_mov_b32_e32 v63, v143
	v_mov_b32_e32 v64, v143
	v_mov_b32_e32 v65, v143
	v_mov_b32_e32 v66, v143
	v_mov_b32_e32 v67, v143
	v_mov_b32_e32 v68, v143
	v_mov_b32_e32 v69, v143
	v_mov_b32_e32 v70, v143
	v_mov_b32_e32 v71, v143
	v_mov_b32_e32 v72, v143
	v_mov_b32_e32 v73, v143
	v_mov_b32_e32 v74, v143
	v_mov_b32_e32 v75, v143
	v_mov_b32_e32 v76, v143
	v_mov_b32_e32 v77, v143
	v_mov_b32_e32 v78, v143
	v_mov_b32_e32 v79, v143
	v_mov_b32_e32 v80, v143
	v_mov_b32_e32 v81, v143
	v_mov_b32_e32 v82, v143
	v_mov_b32_e32 v83, v143
	v_mov_b32_e32 v84, v143
	v_mov_b32_e32 v85, v143
	v_mov_b32_e32 v86, v143
	v_mov_b32_e32 v87, v143
	v_mov_b32_e32 v88, v143
	v_mov_b32_e32 v89, v143
	v_mov_b32_e32 v90, v143
	v_mov_b32_e32 v91, v143
	v_mov_b32_e32 v92, v143
	v_mov_b32_e32 v93, v143
	v_mov_b32_e32 v94, v143
	v_mov_b32_e32 v95, v143
	v_mov_b32_e32 v96, v143
	v_mov_b32_e32 v97, v143
	v_mov_b32_e32 v98, v143
	v_mov_b32_e32 v99, v143
	v_mov_b32_e32 v100, v143
	v_mov_b32_e32 v101, v143
	v_mov_b32_e32 v102, v143
	v_mov_b32_e32 v103, v143
	v_mov_b32_e32 v104, v143
	v_mov_b32_e32 v105, v143
	v_mov_b32_e32 v106, v143
	v_mov_b32_e32 v107, v143
	v_mov_b32_e32 v108, v143
	v_mov_b32_e32 v109, v143
	v_mov_b32_e32 v110, v143
	v_mov_b32_e32 v111, v143
	v_mov_b32_e32 v112, v143
	v_mov_b32_e32 v113, v143
	v_mov_b32_e32 v114, v143
	v_mov_b32_e32 v115, v143
	v_mov_b32_e32 v116, v143
	v_mov_b32_e32 v117, v143
	v_mov_b32_e32 v118, v143
	v_mov_b32_e32 v119, v143
	v_mov_b32_e32 v120, v143
	v_mov_b32_e32 v121, v143
	v_mov_b32_e32 v122, v143
	v_mov_b32_e32 v123, v143
	v_mov_b32_e32 v124, v143
	v_mov_b32_e32 v125, v143
	v_mov_b32_e32 v126, v143
	v_mov_b32_e32 v127, v143
	v_mov_b32_e32 v128, v143
	v_mov_b32_e32 v129, v143
	.p2align 6

; #define LAS __attribute__((address_space(3)))
; #define GLDS_STAGE(st, kt_) do { \
;         _Pragma("unroll") for (int i_ = 0; i_ < FI; ++i_) { \
;             glds16(ap + (size_t)(32 * i_) * lda + (kt_) * 64, l3a + (st) + tid * 16 + i_ * 4096); \
;             glds16(bp + (size_t)(32 * i_) * ldb + (kt_) * 64, l3a + (st) + OPB + tid * 16 + i_ * 4096); } } while (0)
; #define GLDS_STAGE(st, kt_) do { \
;         _Pragma("unroll") for (int i_ = 0; i_ < 4; ++i_) { \
;             glds16(ap + (size_t)(64 * i_) * lda + (kt_) * 64, l3a + (st) + tid * 16 + i_ * 8192); \
;             glds16(bp + (size_t)(64 * i_) * ldb + (kt_) * 64, l3a + (st) + 32768 + tid * 16 + i_ * 8192); } } while (0)
; template <class Epi>
; DEV void gemm256_tile(const bf16_t* __restrict__ A, int lda, const bf16_t* __restrict__ Bt, int ldb, int K, unsigned char* lds, const Epi& epi) {
;     int tid = threadIdx.x; asm volatile("" : "+v"(tid)); const int lane = tid & 63, wid = tid >> 6;
;     const int wr = wid >> 2, wc = wid & 3, fr = lane & 15, fq = lane >> 4;
;     f32x4 acc[8][4];
; #pragma unroll
;     for (int i = 0; i < 8; ++i)
; #pragma unroll
;         for (int j = 0; j < 4; ++j) acc[i][j] = (f32x4){0.f, 0.f, 0.f, 0.f};
;     const int lrow = tid >> 3, lcs = (tid & 7) ^ (lrow & 7);
;     const bf16_t* ap = A + (size_t)lrow * lda + lcs * 8;
;     const bf16_t* bp = Bt + (size_t)lrow * ldb + lcs * 8;
;     const unsigned l3a = (unsigned)(size_t)(LAS unsigned char*)lds;
;     const int nk = K >> 6;
;     ...
;     GLDS_STAGE(0, 0);
;     const int aoff = (wr * 128 + fr) * 128, boff = 32768 + (wc * 64 + fr) * 128, sw = fr & 7;
.LBB0_1002:
	s_lshl_b32 s14, s23, 5
	s_and_b32 s14, s14, 0xe0
	s_ashr_i32 s15, s23, 3
	s_add_i32 s14, s14, s15
	s_ashr_i32 s15, s14, 31
	s_lshr_b32 s15, s15, 26
	s_add_i32 s15, s14, s15
	s_ashr_i32 s16, s15, 6
	s_and_b32 s15, s15, 0xffc0
	s_sub_i32 s14, s14, s15
	s_bfe_i32 s15, s14, 0x80000
	s_bfe_u32 s15, s15, 0x3000c
	s_add_i32 s15, s14, s15
	s_bfe_i32 s17, s15, 0x80000
	s_and_b32 s15, s15, 0xf8
	s_sub_i32 s14, s14, s15
	v_mov_b32_e32 v142, v0
	s_lshl_b32 s16, s16, 3
	s_sext_i32_i16 s25, s17
	s_sext_i32_i8 s14, s14
	s_add_i32 s16, s16, s14
	v_ashrrev_i32_e32 v10, 3, v142
	s_ashr_i32 s14, s25, 3
	v_xor_b32_e32 v8, v10, v142
	v_mad_i64_i32 v[2:3], s[26:27], s16, v1, v[174:175]
	v_mad_i64_i32 v[4:5], s[26:27], s14, v1, v[170:171]
	v_lshlrev_b32_e32 v8, 4, v8
	v_mad_i64_i32 v[2:3], s[26:27], v10, s21, v[2:3]
	v_and_b32_e32 v136, 0x70, v8
	v_mad_i64_i32 v[4:5], s[26:27], v10, s21, v[4:5]
	v_lshl_add_u64 v[2:3], v[2:3], 0, v[136:137]
	v_lshl_add_u64 v[4:5], v[4:5], 0, v[136:137]
	v_lshlrev_b32_e32 v136, 4, v142
	s_lshr_b32 s24, s25, 3
	v_add_u32_e32 v150, 0x8000, v136
	v_readfirstlane_b32 s15, v136
	s_mov_b32 s25, m0
	s_mov_b32 m0, s15
	s_nop 0
	global_load_lds_dwordx4 v[2:3], off
	s_mov_b32 m0, s25
	v_lshl_add_u64 v[8:9], v[2:3], 0, s[6:7]
	v_readfirstlane_b32 s25, v150
	s_mov_b32 s26, m0
	s_mov_b32 m0, s25
	s_nop 0
	global_load_lds_dwordx4 v[4:5], off
	s_mov_b32 m0, s26
	s_add_i32 s25, s15, 0x2000
	s_mov_b32 s26, m0
	s_mov_b32 m0, s25
	s_nop 0
	global_load_lds_dwordx4 v[8:9], off
	s_mov_b32 m0, s26
	v_lshl_add_u64 v[8:9], v[4:5], 0, s[6:7]
	s_add_i32 s25, s15, 0xa000
	s_mov_b32 s26, m0
	s_mov_b32 m0, s25
	s_nop 0
	global_load_lds_dwordx4 v[8:9], off
	s_mov_b32 m0, s26
	v_lshl_add_u64 v[8:9], v[2:3], 0, s[8:9]
	s_add_i32 s25, s15, 0x4000
	s_mov_b32 s26, m0
	s_mov_b32 m0, s25
	s_nop 0
	global_load_lds_dwordx4 v[8:9], off
	s_mov_b32 m0, s26
	v_lshl_add_u64 v[8:9], v[4:5], 0, s[8:9]
	s_add_i32 s25, s15, 0xc000
	s_mov_b32 s26, m0
	s_mov_b32 m0, s25
	s_nop 0
	global_load_lds_dwordx4 v[8:9], off
	s_mov_b32 m0, s26
	v_lshl_add_u64 v[2:3], v[2:3], 0, s[10:11]
	s_add_i32 s25, s15, 0x6000
	s_mov_b32 s26, m0
	s_mov_b32 m0, s25
	s_nop 0
	global_load_lds_dwordx4 v[2:3], off
	s_mov_b32 m0, s26
	v_lshl_add_u64 v[2:3], v[4:5], 0, s[10:11]
	v_and_b32_e32 v143, 15, v142
	s_add_i32 s15, s15, 0xe000
	s_mov_b32 s25, m0
	s_mov_b32 m0, s15
	s_nop 0
	global_load_lds_dwordx4 v[2:3], off
	s_mov_b32 m0, s25
	v_ashrrev_i32_e32 v2, 1, v142
	v_and_or_b32 v146, v2, s22, v143
	v_lshlrev_b32_e32 v2, 7, v142
	v_lshrrev_b32_e32 v144, 4, v142
	v_bfe_u32 v145, v142, 4, 2
	v_and_b32_e32 v151, 0x6780, v2
	v_and_b32_e32 v2, 7, v142
	v_mad_i64_i32 v[6:7], s[26:27], v10, s21, 0
	v_bitop3_b32 v3, v144, v2, 3 bitop3:0x6c
	v_bitop3_b32 v2, v145, v2, 4 bitop3:0x36
	v_bitop3_b32 v4, v10, 7, v142 bitop3:0x48
	v_lshlrev_b32_e32 v149, 4, v3
	v_lshlrev_b32_e32 v147, 4, v2
	v_mad_i64_i32 v[2:3], s[26:27], s16, v1, v[6:7]
	v_lshlrev_b32_e32 v4, 4, v4
	v_or_b32_e32 v2, v2, v4
	v_lshl_add_u64 v[138:139], v[132:133], 0, v[2:3]
	v_mad_i64_i32 v[2:3], s[26:27], s14, v1, v[6:7]
	v_or_b32_e32 v2, v2, v4
	s_ashr_i32 s17, s16, 31
	s_mul_hi_i32 s19, s16, 0x108000
	s_mul_i32 s18, s16, 0x108000
	v_lshlrev_b32_e32 v148, 7, v146
	v_lshl_add_u64 v[140:141], v[134:135], 0, v[2:3]
	s_mov_b32 s25, 0
	v_mov_b32_e32 v38, v137
	v_mov_b32_e32 v39, v137
	v_mov_b32_e32 v40, v137
	v_mov_b32_e32 v41, v137
	v_mov_b32_e32 v2, v137
	v_mov_b32_e32 v3, v137
	v_mov_b32_e32 v4, v137
	v_mov_b32_e32 v5, v137
	v_mov_b32_e32 v6, v137
	v_mov_b32_e32 v7, v137
	v_mov_b32_e32 v8, v137
	v_mov_b32_e32 v9, v137
	v_mov_b32_e32 v10, v137
	v_mov_b32_e32 v11, v137
	v_mov_b32_e32 v12, v137
	v_mov_b32_e32 v13, v137
	v_mov_b32_e32 v14, v137
	v_mov_b32_e32 v15, v137
	v_mov_b32_e32 v16, v137
	v_mov_b32_e32 v17, v137
	v_mov_b32_e32 v18, v137
	v_mov_b32_e32 v19, v137
	v_mov_b32_e32 v20, v137
	v_mov_b32_e32 v21, v137
	v_mov_b32_e32 v22, v137
	v_mov_b32_e32 v23, v137
	v_mov_b32_e32 v24, v137
	v_mov_b32_e32 v25, v137
	v_mov_b32_e32 v26, v137
	v_mov_b32_e32 v27, v137
	v_mov_b32_e32 v28, v137
	v_mov_b32_e32 v29, v137
	v_mov_b32_e32 v30, v137
	v_mov_b32_e32 v31, v137
	v_mov_b32_e32 v32, v137
	v_mov_b32_e32 v33, v137
	v_mov_b32_e32 v34, v137
	v_mov_b32_e32 v35, v137
	v_mov_b32_e32 v36, v137
	v_mov_b32_e32 v37, v137
	v_mov_b32_e32 v42, v137
	v_mov_b32_e32 v43, v137
	v_mov_b32_e32 v44, v137
	v_mov_b32_e32 v45, v137
	v_mov_b32_e32 v46, v137
	v_mov_b32_e32 v47, v137
	v_mov_b32_e32 v48, v137
	v_mov_b32_e32 v49, v137
	v_mov_b32_e32 v50, v137
	v_mov_b32_e32 v51, v137
	v_mov_b32_e32 v52, v137
	v_mov_b32_e32 v53, v137
	v_mov_b32_e32 v54, v137
	v_mov_b32_e32 v55, v137
	v_mov_b32_e32 v56, v137
	v_mov_b32_e32 v57, v137
	v_mov_b32_e32 v58, v137
	v_mov_b32_e32 v59, v137
	v_mov_b32_e32 v60, v137
	v_mov_b32_e32 v61, v137
	v_mov_b32_e32 v62, v137
	v_mov_b32_e32 v63, v137
	v_mov_b32_e32 v64, v137
	v_mov_b32_e32 v65, v137
	v_mov_b32_e32 v66, v137
	v_mov_b32_e32 v67, v137
	v_mov_b32_e32 v68, v137
	v_mov_b32_e32 v69, v137
	v_mov_b32_e32 v70, v137
	v_mov_b32_e32 v71, v137
	v_mov_b32_e32 v72, v137
	v_mov_b32_e32 v73, v137
	v_mov_b32_e32 v74, v137
	v_mov_b32_e32 v75, v137
	v_mov_b32_e32 v76, v137
	v_mov_b32_e32 v77, v137
	v_mov_b32_e32 v78, v137
	v_mov_b32_e32 v79, v137
	v_mov_b32_e32 v80, v137
	v_mov_b32_e32 v81, v137
	v_mov_b32_e32 v82, v137
	v_mov_b32_e32 v83, v137
	v_mov_b32_e32 v84, v137
	v_mov_b32_e32 v85, v137
	v_mov_b32_e32 v86, v137
	v_mov_b32_e32 v87, v137
	v_mov_b32_e32 v88, v137
	v_mov_b32_e32 v89, v137
	v_mov_b32_e32 v90, v137
	v_mov_b32_e32 v91, v137
	v_mov_b32_e32 v92, v137
	v_mov_b32_e32 v93, v137
	v_mov_b32_e32 v94, v137
	v_mov_b32_e32 v95, v137
	v_mov_b32_e32 v96, v137
	v_mov_b32_e32 v97, v137
	v_mov_b32_e32 v98, v137
	v_mov_b32_e32 v99, v137
	v_mov_b32_e32 v100, v137
	v_mov_b32_e32 v101, v137
	v_mov_b32_e32 v102, v137
	v_mov_b32_e32 v103, v137
	v_mov_b32_e32 v104, v137
	v_mov_b32_e32 v105, v137
	v_mov_b32_e32 v106, v137
	v_mov_b32_e32 v107, v137
	v_mov_b32_e32 v108, v137
	v_mov_b32_e32 v109, v137
	v_mov_b32_e32 v110, v137
	v_mov_b32_e32 v111, v137
	v_mov_b32_e32 v112, v137
	v_mov_b32_e32 v113, v137
	v_mov_b32_e32 v114, v137
	v_mov_b32_e32 v115, v137
	v_mov_b32_e32 v116, v137
	v_mov_b32_e32 v117, v137
	v_mov_b32_e32 v118, v137
	v_mov_b32_e32 v119, v137
	v_mov_b32_e32 v120, v137
	v_mov_b32_e32 v121, v137
	v_mov_b32_e32 v122, v137
	v_mov_b32_e32 v123, v137
	v_mov_b32_e32 v124, v137
	v_mov_b32_e32 v125, v137
	v_mov_b32_e32 v126, v137
	v_mov_b32_e32 v127, v137
	v_mov_b32_e32 v128, v137
	v_mov_b32_e32 v129, v137
	.p2align 6

; #define LAS __attribute__((address_space(3)))
; #define GLDS_STAGE(st, kt_) do { \
;         _Pragma("unroll") for (int i_ = 0; i_ < FI; ++i_) { \
;             glds16(ap + (size_t)(32 * i_) * lda + (kt_) * 64, l3a + (st) + tid * 16 + i_ * 4096); \
;             glds16(bp + (size_t)(32 * i_) * ldb + (kt_) * 64, l3a + (st) + OPB + tid * 16 + i_ * 4096); } } while (0)
; #define GLDS_STAGE(st, kt_) do { \
;         _Pragma("unroll") for (int i_ = 0; i_ < 4; ++i_) { \
;             glds16(ap + (size_t)(64 * i_) * lda + (kt_) * 64, l3a + (st) + tid * 16 + i_ * 8192); \
;             glds16(bp + (size_t)(64 * i_) * ldb + (kt_) * 64, l3a + (st) + 32768 + tid * 16 + i_ * 8192); } } while (0)
; template <class Epi>
; DEV void gemm256_tile(const bf16_t* __restrict__ A, int lda, const bf16_t* __restrict__ Bt, int ldb, int K, unsigned char* lds, const Epi& epi) {
;     int tid = threadIdx.x; asm volatile("" : "+v"(tid)); const int lane = tid & 63, wid = tid >> 6;
;     const int wr = wid >> 2, wc = wid & 3, fr = lane & 15, fq = lane >> 4;
;     f32x4 acc[8][4];
; #pragma unroll
;     for (int i = 0; i < 8; ++i)
; #pragma unroll
;         for (int j = 0; j < 4; ++j) acc[i][j] = (f32x4){0.f, 0.f, 0.f, 0.f};
;     const int lrow = tid >> 3, lcs = (tid & 7) ^ (lrow & 7);
;     const bf16_t* ap = A + (size_t)lrow * lda + lcs * 8;
;     const bf16_t* bp = Bt + (size_t)lrow * ldb + lcs * 8;
;     const unsigned l3a = (unsigned)(size_t)(LAS unsigned char*)lds;
;     const int nk = K >> 6;
;     ...
;     GLDS_STAGE(0, 0);
;     const int aoff = (wr * 128 + fr) * 128, boff = 32768 + (wc * 64 + fr) * 128, sw = fr & 7;
.LBB0_1235:
	s_lshl_b32 s12, s19, 5
	s_and_b32 s12, s12, 0xe0
	s_ashr_i32 s13, s19, 3
	s_add_i32 s12, s12, s13
	s_ashr_i32 s13, s12, 31
	s_lshr_b32 s13, s13, 26
	s_add_i32 s13, s12, s13
	s_ashr_i32 s14, s13, 6
	s_and_b32 s13, s13, 0xffc0
	s_sub_i32 s12, s12, s13
	s_bfe_i32 s13, s12, 0x80000
	s_bfe_u32 s13, s13, 0x3000c
	s_add_i32 s13, s12, s13
	s_bfe_i32 s15, s13, 0x80000
	s_and_b32 s13, s13, 0xf8
	s_sub_i32 s12, s12, s13
	v_mov_b32_e32 v144, v0
	s_lshl_b32 s14, s14, 3
	s_sext_i32_i16 s15, s15
	s_sext_i32_i8 s12, s12
	s_lshr_b32 s20, s15, 3
	v_ashrrev_i32_e32 v10, 3, v144
	s_add_i32 s14, s14, s12
	s_ashr_i32 s15, s15, 3
	v_xor_b32_e32 v8, v10, v144
	v_mad_i64_i32 v[2:3], s[22:23], s14, v1, v[166:167]
	v_mad_i64_i32 v[4:5], s[22:23], s15, v1, v[164:165]
	v_lshlrev_b32_e32 v8, 4, v8
	v_mad_i64_i32 v[2:3], s[22:23], v10, s16, v[2:3]
	v_and_b32_e32 v138, 0x70, v8
	v_mad_i64_i32 v[4:5], s[22:23], v10, s16, v[4:5]
	v_lshl_add_u64 v[2:3], v[2:3], 0, v[138:139]
	v_lshl_add_u64 v[4:5], v[4:5], 0, v[138:139]
	v_lshlrev_b32_e32 v138, 4, v144
	v_mad_i64_i32 v[6:7], s[22:23], v10, s16, 0
	v_add_u32_e32 v150, 0x8000, v138
	v_readfirstlane_b32 s21, v138
	s_mov_b32 s22, m0
	s_mov_b32 m0, s21
	s_nop 0
	global_load_lds_dwordx4 v[2:3], off
	s_mov_b32 m0, s22
	v_lshl_add_u64 v[8:9], v[2:3], 0, s[4:5]
	v_readfirstlane_b32 s22, v150
	s_mov_b32 s23, m0
	s_mov_b32 m0, s22
	s_nop 0
	global_load_lds_dwordx4 v[4:5], off
	s_mov_b32 m0, s23
	s_add_i32 s22, s21, 0x2000
	s_mov_b32 s23, m0
	s_mov_b32 m0, s22
	s_nop 0
	global_load_lds_dwordx4 v[8:9], off
	s_mov_b32 m0, s23
	v_lshl_add_u64 v[8:9], v[4:5], 0, s[4:5]
	s_add_i32 s22, s21, 0xa000
	s_mov_b32 s23, m0
	s_mov_b32 m0, s22
	s_nop 0
	global_load_lds_dwordx4 v[8:9], off
	s_mov_b32 m0, s23
	v_lshl_add_u64 v[8:9], v[2:3], 0, s[6:7]
	s_add_i32 s22, s21, 0x4000
	s_mov_b32 s23, m0
	s_mov_b32 m0, s22
	s_nop 0
	global_load_lds_dwordx4 v[8:9], off
	s_mov_b32 m0, s23
	v_lshl_add_u64 v[8:9], v[4:5], 0, s[6:7]
	s_add_i32 s22, s21, 0xc000
	s_mov_b32 s23, m0
	s_mov_b32 m0, s22
	s_nop 0
	global_load_lds_dwordx4 v[8:9], off
	s_mov_b32 m0, s23
	v_lshl_add_u64 v[2:3], v[2:3], 0, s[8:9]
	s_add_i32 s22, s21, 0x6000
	s_mov_b32 s23, m0
	s_mov_b32 m0, s22
	s_nop 0
	global_load_lds_dwordx4 v[2:3], off
	s_mov_b32 m0, s23
	v_lshl_add_u64 v[2:3], v[4:5], 0, s[8:9]
	v_and_b32_e32 v145, 15, v144
	s_add_i32 s21, s21, 0xe000
	s_mov_b32 s22, m0
	s_mov_b32 m0, s21
	s_nop 0
	global_load_lds_dwordx4 v[2:3], off
	s_mov_b32 m0, s22
	v_ashrrev_i32_e32 v2, 1, v144
	v_and_or_b32 v148, v2, s18, v145
	v_lshlrev_b32_e32 v2, 7, v144
	v_lshrrev_b32_e32 v146, 4, v144
	v_bfe_u32 v147, v144, 4, 2
	v_and_b32_e32 v153, 0x6780, v2
	v_and_b32_e32 v2, 7, v144
	v_bitop3_b32 v3, v146, v2, 3 bitop3:0x6c
	v_bitop3_b32 v2, v147, v2, 4 bitop3:0x36
	v_bitop3_b32 v4, v10, 7, v144 bitop3:0x48
	v_lshlrev_b32_e32 v152, 4, v3
	v_lshlrev_b32_e32 v149, 4, v2
	v_mad_i64_i32 v[2:3], s[22:23], s14, v1, v[6:7]
	v_lshlrev_b32_e32 v4, 4, v4
	v_or_b32_e32 v2, v2, v4
	v_lshl_add_u64 v[140:141], v[134:135], 0, v[2:3]
	v_mad_i64_i32 v[2:3], s[22:23], s15, v1, v[6:7]
	v_or_b32_e32 v2, v2, v4
	s_mul_hi_i32 s13, s14, 0x108000
	s_mul_i32 s12, s14, 0x108000
	v_lshlrev_b32_e32 v151, 7, v148
	v_lshl_add_u64 v[142:143], v[136:137], 0, v[2:3]
	s_mov_b32 s21, 0
	v_mov_b32_e32 v38, v139
	v_mov_b32_e32 v39, v139
	v_mov_b32_e32 v40, v139
	v_mov_b32_e32 v41, v139
	v_mov_b32_e32 v2, v139
	v_mov_b32_e32 v3, v139
	v_mov_b32_e32 v4, v139
	v_mov_b32_e32 v5, v139
	v_mov_b32_e32 v6, v139
	v_mov_b32_e32 v7, v139
	v_mov_b32_e32 v8, v139
	v_mov_b32_e32 v9, v139
	v_mov_b32_e32 v10, v139
	v_mov_b32_e32 v11, v139
	v_mov_b32_e32 v12, v139
	v_mov_b32_e32 v13, v139
	v_mov_b32_e32 v14, v139
	v_mov_b32_e32 v15, v139
	v_mov_b32_e32 v16, v139
	v_mov_b32_e32 v17, v139
	v_mov_b32_e32 v18, v139
	v_mov_b32_e32 v19, v139
	v_mov_b32_e32 v20, v139
	v_mov_b32_e32 v21, v139
	v_mov_b32_e32 v22, v139
	v_mov_b32_e32 v23, v139
	v_mov_b32_e32 v24, v139
	v_mov_b32_e32 v25, v139
	v_mov_b32_e32 v26, v139
	v_mov_b32_e32 v27, v139
	v_mov_b32_e32 v28, v139
	v_mov_b32_e32 v29, v139
	v_mov_b32_e32 v30, v139
	v_mov_b32_e32 v31, v139
	v_mov_b32_e32 v32, v139
	v_mov_b32_e32 v33, v139
	v_mov_b32_e32 v34, v139
	v_mov_b32_e32 v35, v139
	v_mov_b32_e32 v36, v139
	v_mov_b32_e32 v37, v139
	v_mov_b32_e32 v42, v139
	v_mov_b32_e32 v43, v139
	v_mov_b32_e32 v44, v139
	v_mov_b32_e32 v45, v139
	v_mov_b32_e32 v46, v139
	v_mov_b32_e32 v47, v139
	v_mov_b32_e32 v48, v139
	v_mov_b32_e32 v49, v139
	v_mov_b32_e32 v50, v139
	v_mov_b32_e32 v51, v139
	v_mov_b32_e32 v52, v139
	v_mov_b32_e32 v53, v139
	v_mov_b32_e32 v54, v139
	v_mov_b32_e32 v55, v139
	v_mov_b32_e32 v56, v139
	v_mov_b32_e32 v57, v139
	v_mov_b32_e32 v58, v139
	v_mov_b32_e32 v59, v139
	v_mov_b32_e32 v60, v139
	v_mov_b32_e32 v61, v139
	v_mov_b32_e32 v62, v139
	v_mov_b32_e32 v63, v139
	v_mov_b32_e32 v64, v139
	v_mov_b32_e32 v65, v139
	v_mov_b32_e32 v66, v139
	v_mov_b32_e32 v67, v139
	v_mov_b32_e32 v68, v139
	v_mov_b32_e32 v69, v139
	v_mov_b32_e32 v70, v139
	v_mov_b32_e32 v71, v139
	v_mov_b32_e32 v72, v139
	v_mov_b32_e32 v73, v139
	v_mov_b32_e32 v74, v139
	v_mov_b32_e32 v75, v139
	v_mov_b32_e32 v76, v139
	v_mov_b32_e32 v77, v139
	v_mov_b32_e32 v78, v139
	v_mov_b32_e32 v79, v139
	v_mov_b32_e32 v80, v139
	v_mov_b32_e32 v81, v139
	v_mov_b32_e32 v82, v139
	v_mov_b32_e32 v83, v139
	v_mov_b32_e32 v84, v139
	v_mov_b32_e32 v85, v139
	v_mov_b32_e32 v86, v139
	v_mov_b32_e32 v87, v139
	v_mov_b32_e32 v88, v139
	v_mov_b32_e32 v89, v139
	v_mov_b32_e32 v90, v139
	v_mov_b32_e32 v91, v139
	v_mov_b32_e32 v92, v139
	v_mov_b32_e32 v93, v139
	v_mov_b32_e32 v94, v139
	v_mov_b32_e32 v95, v139
	v_mov_b32_e32 v96, v139
	v_mov_b32_e32 v97, v139
	v_mov_b32_e32 v98, v139
	v_mov_b32_e32 v99, v139
	v_mov_b32_e32 v100, v139
	v_mov_b32_e32 v101, v139
	v_mov_b32_e32 v102, v139
	v_mov_b32_e32 v103, v139
	v_mov_b32_e32 v104, v139
	v_mov_b32_e32 v105, v139
	v_mov_b32_e32 v106, v139
	v_mov_b32_e32 v107, v139
	v_mov_b32_e32 v108, v139
	v_mov_b32_e32 v109, v139
	v_mov_b32_e32 v110, v139
	v_mov_b32_e32 v111, v139
	v_mov_b32_e32 v112, v139
	v_mov_b32_e32 v113, v139
	v_mov_b32_e32 v114, v139
	v_mov_b32_e32 v115, v139
	v_mov_b32_e32 v116, v139
	v_mov_b32_e32 v117, v139
	v_mov_b32_e32 v118, v139
	v_mov_b32_e32 v119, v139
	v_mov_b32_e32 v120, v139
	v_mov_b32_e32 v121, v139
	v_mov_b32_e32 v122, v139
	v_mov_b32_e32 v123, v139
	v_mov_b32_e32 v124, v139
	v_mov_b32_e32 v125, v139
	v_mov_b32_e32 v126, v139
	v_mov_b32_e32 v127, v139
	v_mov_b32_e32 v128, v139
	v_mov_b32_e32 v129, v139
	.p2align 6

; #define LAS __attribute__((address_space(3)))
; #define GLDS_STAGE(st, kt_) do { \
;         _Pragma("unroll") for (int i_ = 0; i_ < FI; ++i_) { \
;             glds16(ap + (size_t)(32 * i_) * lda + (kt_) * 64, l3a + (st) + tid * 16 + i_ * 4096); \
;             glds16(bp + (size_t)(32 * i_) * ldb + (kt_) * 64, l3a + (st) + OPB + tid * 16 + i_ * 4096); } } while (0)
; #define GLDS_STAGE(st, kt_) do { \
;         _Pragma("unroll") for (int i_ = 0; i_ < 4; ++i_) { \
;             glds16(ap + (size_t)(64 * i_) * lda + (kt_) * 64, l3a + (st) + tid * 16 + i_ * 8192); \
;             glds16(bp + (size_t)(64 * i_) * ldb + (kt_) * 64, l3a + (st) + 32768 + tid * 16 + i_ * 8192); } } while (0)
; template <class Epi>
; DEV void gemm256_tile(const bf16_t* __restrict__ A, int lda, const bf16_t* __restrict__ Bt, int ldb, int K, unsigned char* lds, const Epi& epi) {
;     int tid = threadIdx.x; asm volatile("" : "+v"(tid)); const int lane = tid & 63, wid = tid >> 6;
;     const int wr = wid >> 2, wc = wid & 3, fr = lane & 15, fq = lane >> 4;
;     f32x4 acc[8][4];
; #pragma unroll
;     for (int i = 0; i < 8; ++i)
; #pragma unroll
;         for (int j = 0; j < 4; ++j) acc[i][j] = (f32x4){0.f, 0.f, 0.f, 0.f};
;     const int lrow = tid >> 3, lcs = (tid & 7) ^ (lrow & 7);
;     const bf16_t* ap = A + (size_t)lrow * lda + lcs * 8;
;     const bf16_t* bp = Bt + (size_t)lrow * ldb + lcs * 8;
;     const unsigned l3a = (unsigned)(size_t)(LAS unsigned char*)lds;
;     const int nk = K >> 6;
;     ...
;     GLDS_STAGE(0, 0);
;     const int aoff = (wr * 128 + fr) * 128, boff = 32768 + (wc * 64 + fr) * 128, sw = fr & 7;
.LBB0_1465:
	s_lshl_b32 s12, s19, 5
	s_and_b32 s12, s12, 0xe0
	s_ashr_i32 s13, s19, 3
	s_add_i32 s12, s12, s13
	s_ashr_i32 s13, s12, 31
	s_lshr_b32 s13, s13, 26
	s_add_i32 s13, s12, s13
	s_ashr_i32 s14, s13, 6
	s_and_b32 s13, s13, 0xffc0
	s_sub_i32 s12, s12, s13
	s_bfe_i32 s13, s12, 0x80000
	s_bfe_u32 s13, s13, 0x3000c
	s_add_i32 s13, s12, s13
	s_bfe_i32 s15, s13, 0x80000
	s_and_b32 s13, s13, 0xf8
	s_sub_i32 s12, s12, s13
	v_mov_b32_e32 v146, v0
	s_lshl_b32 s14, s14, 3
	s_sext_i32_i16 s15, s15
	s_sext_i32_i8 s12, s12
	s_lshr_b32 s20, s15, 3
	v_ashrrev_i32_e32 v10, 3, v146
	s_add_i32 s14, s14, s12
	s_ashr_i32 s15, s15, 3
	v_xor_b32_e32 v8, v10, v146
	v_mad_i64_i32 v[2:3], s[22:23], s14, v1, v[132:133]
	v_mad_i64_i32 v[4:5], s[22:23], s15, v1, v[160:161]
	v_lshlrev_b32_e32 v8, 4, v8
	v_mad_i64_i32 v[2:3], s[22:23], v10, s17, v[2:3]
	v_and_b32_e32 v140, 0x70, v8
	v_mad_i64_i32 v[4:5], s[22:23], v10, s17, v[4:5]
	v_lshl_add_u64 v[2:3], v[2:3], 0, v[140:141]
	v_lshl_add_u64 v[4:5], v[4:5], 0, v[140:141]
	v_lshlrev_b32_e32 v140, 4, v146
	v_mad_i64_i32 v[6:7], s[22:23], v10, s17, 0
	v_add_u32_e32 v153, 0x8000, v140
	v_readfirstlane_b32 s21, v140
	s_mov_b32 s22, m0
	s_mov_b32 m0, s21
	s_nop 0
	global_load_lds_dwordx4 v[2:3], off
	s_mov_b32 m0, s22
	v_lshl_add_u64 v[8:9], v[2:3], 0, s[4:5]
	v_readfirstlane_b32 s22, v153
	s_mov_b32 s23, m0
	s_mov_b32 m0, s22
	s_nop 0
	global_load_lds_dwordx4 v[4:5], off
	s_mov_b32 m0, s23
	s_add_i32 s22, s21, 0x2000
	s_mov_b32 s23, m0
	s_mov_b32 m0, s22
	s_nop 0
	global_load_lds_dwordx4 v[8:9], off
	s_mov_b32 m0, s23
	v_lshl_add_u64 v[8:9], v[4:5], 0, s[4:5]
	s_add_i32 s22, s21, 0xa000
	s_mov_b32 s23, m0
	s_mov_b32 m0, s22
	s_nop 0
	global_load_lds_dwordx4 v[8:9], off
	s_mov_b32 m0, s23
	v_lshl_add_u64 v[8:9], v[2:3], 0, s[6:7]
	s_add_i32 s22, s21, 0x4000
	s_mov_b32 s23, m0
	s_mov_b32 m0, s22
	s_nop 0
	global_load_lds_dwordx4 v[8:9], off
	s_mov_b32 m0, s23
	v_lshl_add_u64 v[8:9], v[4:5], 0, s[6:7]
	s_add_i32 s22, s21, 0xc000
	s_mov_b32 s23, m0
	s_mov_b32 m0, s22
	s_nop 0
	global_load_lds_dwordx4 v[8:9], off
	s_mov_b32 m0, s23
	v_lshl_add_u64 v[2:3], v[2:3], 0, s[8:9]
	s_add_i32 s22, s21, 0x6000
	s_mov_b32 s23, m0
	s_mov_b32 m0, s22
	s_nop 0
	global_load_lds_dwordx4 v[2:3], off
	s_mov_b32 m0, s23
	v_lshl_add_u64 v[2:3], v[4:5], 0, s[8:9]
	v_and_b32_e32 v147, 15, v146
	s_add_i32 s21, s21, 0xe000
	s_mov_b32 s22, m0
	s_mov_b32 m0, s21
	s_nop 0
	global_load_lds_dwordx4 v[2:3], off
	s_mov_b32 m0, s22
	v_ashrrev_i32_e32 v2, 1, v146
	v_and_or_b32 v150, v2, s18, v147
	v_lshlrev_b32_e32 v2, 7, v146
	v_lshrrev_b32_e32 v148, 4, v146
	v_bfe_u32 v149, v146, 4, 2
	v_and_b32_e32 v155, 0x6780, v2
	v_and_b32_e32 v2, 7, v146
	v_bitop3_b32 v3, v148, v2, 3 bitop3:0x6c
	v_bitop3_b32 v2, v149, v2, 4 bitop3:0x36
	v_bitop3_b32 v4, v10, 7, v146 bitop3:0x48
	v_lshlrev_b32_e32 v154, 4, v3
	v_lshlrev_b32_e32 v151, 4, v2
	v_mad_i64_i32 v[2:3], s[22:23], s14, v1, v[6:7]
	v_lshlrev_b32_e32 v4, 4, v4
	v_or_b32_e32 v2, v2, v4
	v_lshl_add_u64 v[142:143], v[136:137], 0, v[2:3]
	v_mad_i64_i32 v[2:3], s[22:23], s15, v1, v[6:7]
	v_or_b32_e32 v2, v2, v4
	s_mul_hi_i32 s13, s14, 0x108000
	s_mul_i32 s12, s14, 0x108000
	v_lshlrev_b32_e32 v152, 7, v150
	v_lshl_add_u64 v[144:145], v[138:139], 0, v[2:3]
	s_mov_b32 s21, 0
	v_mov_b32_e32 v38, v141
	v_mov_b32_e32 v39, v141
	v_mov_b32_e32 v40, v141
	v_mov_b32_e32 v41, v141
	v_mov_b32_e32 v2, v141
	v_mov_b32_e32 v3, v141
	v_mov_b32_e32 v4, v141
	v_mov_b32_e32 v5, v141
	v_mov_b32_e32 v6, v141
	v_mov_b32_e32 v7, v141
	v_mov_b32_e32 v8, v141
	v_mov_b32_e32 v9, v141
	v_mov_b32_e32 v10, v141
	v_mov_b32_e32 v11, v141
	v_mov_b32_e32 v12, v141
	v_mov_b32_e32 v13, v141
	v_mov_b32_e32 v14, v141
	v_mov_b32_e32 v15, v141
	v_mov_b32_e32 v16, v141
	v_mov_b32_e32 v17, v141
	v_mov_b32_e32 v18, v141
	v_mov_b32_e32 v19, v141
	v_mov_b32_e32 v20, v141
	v_mov_b32_e32 v21, v141
	v_mov_b32_e32 v22, v141
	v_mov_b32_e32 v23, v141
	v_mov_b32_e32 v24, v141
	v_mov_b32_e32 v25, v141
	v_mov_b32_e32 v26, v141
	v_mov_b32_e32 v27, v141
	v_mov_b32_e32 v28, v141
	v_mov_b32_e32 v29, v141
	v_mov_b32_e32 v30, v141
	v_mov_b32_e32 v31, v141
	v_mov_b32_e32 v32, v141
	v_mov_b32_e32 v33, v141
	v_mov_b32_e32 v34, v141
	v_mov_b32_e32 v35, v141
	v_mov_b32_e32 v36, v141
	v_mov_b32_e32 v37, v141
	v_mov_b32_e32 v42, v141
	v_mov_b32_e32 v43, v141
	v_mov_b32_e32 v44, v141
	v_mov_b32_e32 v45, v141
	v_mov_b32_e32 v46, v141
	v_mov_b32_e32 v47, v141
	v_mov_b32_e32 v48, v141
	v_mov_b32_e32 v49, v141
	v_mov_b32_e32 v50, v141
	v_mov_b32_e32 v51, v141
	v_mov_b32_e32 v52, v141
	v_mov_b32_e32 v53, v141
	v_mov_b32_e32 v54, v141
	v_mov_b32_e32 v55, v141
	v_mov_b32_e32 v56, v141
	v_mov_b32_e32 v57, v141
	v_mov_b32_e32 v58, v141
	v_mov_b32_e32 v59, v141
	v_mov_b32_e32 v60, v141
	v_mov_b32_e32 v61, v141
	v_mov_b32_e32 v62, v141
	v_mov_b32_e32 v63, v141
	v_mov_b32_e32 v64, v141
	v_mov_b32_e32 v65, v141
	v_mov_b32_e32 v66, v141
	v_mov_b32_e32 v67, v141
	v_mov_b32_e32 v68, v141
	v_mov_b32_e32 v69, v141
	v_mov_b32_e32 v70, v141
	v_mov_b32_e32 v71, v141
	v_mov_b32_e32 v72, v141
	v_mov_b32_e32 v73, v141
	v_mov_b32_e32 v74, v141
	v_mov_b32_e32 v75, v141
	v_mov_b32_e32 v76, v141
	v_mov_b32_e32 v77, v141
	v_mov_b32_e32 v78, v141
	v_mov_b32_e32 v79, v141
	v_mov_b32_e32 v80, v141
	v_mov_b32_e32 v81, v141
	v_mov_b32_e32 v82, v141
	v_mov_b32_e32 v83, v141
	v_mov_b32_e32 v84, v141
	v_mov_b32_e32 v85, v141
	v_mov_b32_e32 v86, v141
	v_mov_b32_e32 v87, v141
	v_mov_b32_e32 v88, v141
	v_mov_b32_e32 v89, v141
	v_mov_b32_e32 v90, v141
	v_mov_b32_e32 v91, v141
	v_mov_b32_e32 v92, v141
	v_mov_b32_e32 v93, v141
	v_mov_b32_e32 v94, v141
	v_mov_b32_e32 v95, v141
	v_mov_b32_e32 v96, v141
	v_mov_b32_e32 v97, v141
	v_mov_b32_e32 v98, v141
	v_mov_b32_e32 v99, v141
	v_mov_b32_e32 v100, v141
	v_mov_b32_e32 v101, v141
	v_mov_b32_e32 v102, v141
	v_mov_b32_e32 v103, v141
	v_mov_b32_e32 v104, v141
	v_mov_b32_e32 v105, v141
	v_mov_b32_e32 v106, v141
	v_mov_b32_e32 v107, v141
	v_mov_b32_e32 v108, v141
	v_mov_b32_e32 v109, v141
	v_mov_b32_e32 v110, v141
	v_mov_b32_e32 v111, v141
	v_mov_b32_e32 v112, v141
	v_mov_b32_e32 v113, v141
	v_mov_b32_e32 v114, v141
	v_mov_b32_e32 v115, v141
	v_mov_b32_e32 v116, v141
	v_mov_b32_e32 v117, v141
	v_mov_b32_e32 v118, v141
	v_mov_b32_e32 v119, v141
	v_mov_b32_e32 v120, v141
	v_mov_b32_e32 v121, v141
	v_mov_b32_e32 v122, v141
	v_mov_b32_e32 v123, v141
	v_mov_b32_e32 v124, v141
	v_mov_b32_e32 v125, v141
	v_mov_b32_e32 v126, v141
	v_mov_b32_e32 v127, v141
	v_mov_b32_e32 v128, v141
	v_mov_b32_e32 v129, v141
	.p2align 6
